# attention: next unit's Q rows, cumsum slice and first K/V tiles requested at the start of the current unit's epilogue (one extra workgroup barrier), waited for in the next prologue
# speedup vs baseline: 1.1134x; 1.0021x over previous
.LBB0_503:
	v_readlane_b32 s0, v255, 0
	s_cmpk_gt_i32 s0, 0x1ff
	s_cbranch_scc1 .LBB0_564
	s_add_u32 s60, s30, 0x15400400
	s_addc_u32 s61, s31, 0
	s_add_u32 s62, s30, 0xb400000
	s_mov_b32 s38, 0xffff0000
	s_addc_u32 s63, s31, 0
	s_mov_b32 s1, 0
	v_mov_b32_e32 v223, 0
	s_mov_b64 s[6:7], 0x10000
	s_mov_b64 s[22:23], 0x20000
	s_mov_b64 s[24:25], 0x30000
	s_mov_b64 s[36:37], 0x50000
	s_add_i32 s64, 0, 0x14900
	s_mov_b32 s39, -1
	s_mov_b64 s[40:41], 0x40000
	v_mov_b32_e32 v233, 0xff800000
	v_readlane_b32 s0, v255, 0
	s_mov_b32 s65, 0
	s_mov_b32 s67, 0
	v_mbcnt_lo_u32_b32 v252, -1, 0
	v_mbcnt_hi_u32_b32 v252, -1, v252
	v_and_b32_e32 v253, 63, v252
	v_and_b32_e32 v254, 31, v252
	v_bfe_u32 v232, v252, 5, 1
	s_lshr_b32 s71, s67, 1
	s_mul_i32 s71, s71, s84
	v_readlane_b32 s72, v255, 0
	s_mov_b64 s[100:101], 0
	s_add_i32 s71, s71, s72
	s_cmpk_lt_i32 s71, 0x200
	s_cbranch_scc0 .Lattn_pf_done_f
	s_ashr_i32 s72, s71, 2
	s_lshl_b32 s73, s71, 8
	s_and_b32 s73, s73, 0x300
	s_and_b32 s74, s67, 1
	s_xor_b32 s75, s73, 0x700
	s_cmp_eq_u32 s74, 0
	s_cselect_b32 s73, s75, s73
	s_add_i32 s74, s73, 0x100
	v_add_u32_e32 v50, s33, v252
	v_lshlrev_b32_e32 v51, 2, v50
	v_lshlrev_b32_e32 v52, 4, v50
	v_cmp_gt_i32_e32 vcc, s74, v51
	s_lshl_b32 s75, s72, 13
	s_add_u32 s80, s18, s75
	s_addc_u32 s81, s19, 0
	s_and_saveexec_b64 s[76:77], vcc
	s_mov_b64 s[100:101], exec
	global_load_dwordx4 v[100:103], v52, s[80:81]
	v_add_u32_e32 v104, 0x14800, v52
	s_mov_b64 exec, s[76:77]
	s_lshr_b32 s54, s72, 3
	s_and_b32 s55, s72, 7
	s_lshl_b32 s75, s54, 11
	s_or_b32 s75, s75, s73
	s_lshr_b32 s81, s33, 1
	s_add_i32 s75, s75, s81
	s_lshl_b32 s75, s75, 10
	s_lshl_b32 s80, s55, 7
	s_add_i32 s75, s75, s80
	s_add_u32 s80, s3, s75
	s_addc_u32 s81, s66, 0
	v_lshlrev_b32_e32 v50, 10, v254
	v_lshl_or_b32 v50, v232, 4, v50
	global_load_dwordx4 v[140:143], v50, s[80:81] nt
	global_load_dwordx4 v[136:139], v50, s[80:81] offset:32 nt
	global_load_dwordx4 v[132:135], v50, s[80:81] offset:64 nt
	global_load_dwordx4 v[128:131], v50, s[80:81] offset:96 nt
	s_lshl_b32 s56, s54, 21
	s_lshl_b32 s57, s55, 7
	s_add_i32 s56, s56, s57
	s_add_u32 s82, s62, s56
	s_addc_u32 s83, s63, 0
	s_add_u32 s94, s20, s56
	s_addc_u32 s95, s21, 0
	s_add_u32 s88, s82, 0x10000
	s_addc_u32 s89, s83, 0
	s_add_u32 s92, s82, 0x20000
	s_addc_u32 s93, s83, 0
	s_lshr_b32 s57, s33, 2
	v_lshl_add_u32 v53, v253, 10, s57
	s_and_b32 s59, s57, 48
	v_bfe_u32 v54, v252, 2, 4
	v_or_b32_e32 v54, s59, v54
	s_lshr_b32 s59, s33, 8
	v_and_b32_e32 v55, 3, v252
	s_lshl_b32 s59, s59, 6
	v_lshlrev_b32_e32 v55, 4, v55
	v_lshl_add_u32 v54, v54, 10, s59
	s_lshl_b32 s32, s33, 4
	v_add_u32_e32 v54, v54, v55
	s_mov_b32 s27, m0
	s_mov_b32 m0, s32
	s_nop 0
	global_load_lds_dwordx4 v53, s[82:83]
	s_add_i32 m0, s32, 0x6000
	s_nop 0
	global_load_lds_dwordx4 v54, s[94:95]
	s_add_i32 m0, s32, 0x2000
	s_nop 0
	global_load_lds_dwordx4 v53, s[88:89]
	s_add_i32 m0, s32, 0x4000
	s_nop 0
	global_load_lds_dwordx4 v53, s[92:93]
	s_mov_b32 m0, s27

.LBB0_506:
	s_ashr_i32 s4, s0, 2
	s_lshl_b32 s0, s0, 8
	s_and_b32 s0, s0, 0x300
	s_and_b32 s5, s65, 1
	s_xor_b32 s26, s0, 0x700
	s_cmp_eq_u32 s5, 0
	v_mbcnt_lo_u32_b32 v252, -1, 0
	v_mbcnt_hi_u32_b32 v252, -1, v252
	s_cselect_b32 s52, s26, s0
	v_add_u32_e32 v2, s33, v252
	s_add_i32 s53, s52, 0x100
	v_lshlrev_b32_e32 v0, 2, v2
	v_readfirstlane_b32 s68, v2
	s_ashr_i32 s0, s4, 31
	s_lshr_b32 s0, s0, 29
	s_add_i32 s0, s4, s0
	s_ashr_i32 s26, s0, 3
	s_and_b32 s0, s0, -8
	s_ashr_i32 s45, s68, 6
	s_ashr_i32 s27, s26, 31
	s_sub_i32 s44, s4, s0
	s_lshl_b64 s[4:5], s[26:27], 11
	s_lshl_b32 s57, s45, 5
	s_or_b32 s0, s4, s52
	s_ashr_i32 s4, s57, 31
	s_add_u32 s42, s0, s57
	s_addc_u32 s43, s5, s4
	s_lshl_b64 s[4:5], s[42:43], 10
	s_add_u32 s0, s3, s4
	s_addc_u32 s54, s66, s5
	s_lshl_b32 s4, s44, 6
	s_ashr_i32 s5, s4, 31
	s_lshl_b64 s[50:51], s[4:5], 1
	s_add_u32 s4, s0, s50
	s_addc_u32 s5, s54, s51
	s_lshl_b64 s[26:27], s[26:27], 21
	s_add_u32 s0, s62, s26
	s_addc_u32 s55, s63, s27
	s_add_u32 s54, s0, s50
	s_addc_u32 s55, s55, s51
	s_add_u32 s0, s20, s26
	v_and_b32_e32 v253, 63, v252
	s_addc_u32 s27, s21, s27
	s_add_u32 s26, s0, s50
	v_lshlrev_b32_e32 v222, 10, v253
	s_addc_u32 s27, s27, s51
	v_lshl_add_u64 v[0:1], s[54:55], 0, v[222:223]
	s_lshl_b32 s54, s45, 3
	s_ashr_i32 s55, s54, 31
	v_lshl_add_u64 v[224:225], s[54:55], 1, v[0:1]
	s_lshl_b32 s0, s45, 4
	v_bfe_u32 v0, v252, 2, 4
	v_and_or_b32 v0, s0, 48, v0
	v_lshlrev_b32_e32 v222, 10, v0
	s_ashr_i32 s0, s68, 3
	v_lshl_add_u64 v[0:1], s[26:27], 0, v[222:223]
	s_and_b32 s26, s0, 0xffffffe0
	s_ashr_i32 s27, s26, 31
	s_lshl_b32 s56, s45, 10
	v_lshlrev_b32_e32 v2, 3, v252
	s_cmp_lg_u32 0, -1
	v_and_b32_e32 v240, 24, v2
	s_cselect_b32 s0, 0, 0
	v_lshl_add_u64 v[0:1], s[26:27], 1, v[0:1]
	v_lshlrev_b32_e32 v222, 1, v240
	s_add_i32 s69, s56, s0
	v_and_b32_e32 v254, 31, v252
	v_lshl_add_u64 v[48:49], v[0:1], 0, v[222:223]
	s_add_i32 s70, s69, 0x6000
	v_lshl_add_u64 v[0:1], v[224:225], 0, s[6:7]
	v_bfe_u32 v232, v252, 5, 1
	s_add_i32 s0, s69, 0x2000
	v_lshlrev_b32_e32 v0, 10, v254
	v_lshl_or_b32 v2, v232, 4, v0
	s_lshl_b32 s0, s52, 2
	s_add_i32 s67, s0, 0
	v_or_b32_e32 v239, s57, v254
	v_lshl_add_u64 v[0:1], v[224:225], 0, s[22:23]
	s_add_i32 s0, s69, 0x4000
	s_add_i32 s67, s67, 0x14800
	v_lshl_add_u32 v3, v239, 2, s67
	s_cmp_lg_u32 s65, 0
	s_cbranch_scc1 .Lattn_pf_wait
	s_waitcnt vmcnt(0)
.Lattn_pf_wait:
	s_waitcnt vmcnt(4)
	s_mov_b64 s[98:99], exec
	s_mov_b64 exec, s[100:101]
	ds_write_b128 v104, v[100:103]
	s_mov_b64 exec, s[98:99]
	s_waitcnt lgkmcnt(0)
	s_barrier
	ds_read_b32 v0, v3
	v_lshlrev_b32_e32 v1, 10, v232
	v_lshlrev_b32_e32 v2, 4, v254
	v_add3_u32 v241, 0, v1, v2
	s_cmp_lg_u32 s52, 0
	s_waitcnt lgkmcnt(0)
	v_add_f32_e32 v0, 0x41800000, v0
	v_xor_b32_e32 v32, 0x80000000, v0
	v_mov_b32_e32 v33, v32
	v_mov_b32_e32 v34, v32
	v_mov_b32_e32 v35, v32
	v_mov_b32_e32 v36, v32
	v_mov_b32_e32 v37, v32
	v_mov_b32_e32 v38, v32
	v_mov_b32_e32 v39, v32
	v_mov_b32_e32 v40, v32
	v_mov_b32_e32 v41, v32
	v_mov_b32_e32 v42, v32
	v_mov_b32_e32 v43, v32
	v_mov_b32_e32 v44, v32
	v_mov_b32_e32 v45, v32
	v_mov_b32_e32 v46, v32
	v_mov_b32_e32 v47, v32
	ds_read_b128 v[0:3], v241
	ds_read_b128 v[50:53], v241 offset:512
	s_cselect_b64 s[4:5], -1, 0
	v_lshlrev_b32_e32 v222, 2, v232
	s_and_b64 vcc, exec, s[4:5]
	s_waitcnt vmcnt(3) lgkmcnt(1)
	v_mfma_f32_32x32x16_bf16 v[16:31], v[0:3], v[140:143], v[32:47]
	s_waitcnt lgkmcnt(0)
	v_mfma_f32_32x32x16_bf16 v[0:15], v[50:53], v[140:143], v[32:47]
	ds_read_b128 v[50:53], v241 offset:2048
	s_waitcnt vmcnt(2) lgkmcnt(0)
	v_mfma_f32_32x32x16_bf16 v[16:31], v[50:53], v[136:139], v[16:31]
	ds_read_b128 v[50:53], v241 offset:2560
	s_waitcnt lgkmcnt(0)
	v_mfma_f32_32x32x16_bf16 v[0:15], v[50:53], v[136:139], v[0:15]
	ds_read_b128 v[50:53], v241 offset:4096
	s_waitcnt vmcnt(1) lgkmcnt(0)
	v_mfma_f32_32x32x16_bf16 v[16:31], v[50:53], v[132:135], v[16:31]
	ds_read_b128 v[50:53], v241 offset:4608
	s_waitcnt lgkmcnt(0)
	v_mfma_f32_32x32x16_bf16 v[0:15], v[50:53], v[132:135], v[0:15]
	ds_read_b128 v[50:53], v241 offset:6144
	s_waitcnt vmcnt(0) lgkmcnt(0)
	v_mfma_f32_32x32x16_bf16 v[16:31], v[50:53], v[128:131], v[16:31]
	ds_read_b128 v[50:53], v241 offset:6656
	s_waitcnt lgkmcnt(0)
	v_mfma_f32_32x32x16_bf16 v[0:15], v[50:53], v[128:131], v[0:15]
	s_nop 15
	s_nop 7
	s_cbranch_vccnz .LBB0_510
	v_or_b32_e32 v50, 32, v222
	v_cmp_le_i32_e32 vcc, v50, v239
	v_or_b32_e32 v50, 33, v222
	s_nop 7
	v_cndmask_b32_e32 v0, v233, v0, vcc
	v_cmp_lt_i32_e32 vcc, v222, v239
	s_nop 1
	v_cndmask_b32_e32 v17, v233, v17, vcc
	v_cmp_le_i32_e32 vcc, v222, v239
	s_nop 1
	v_cndmask_b32_e32 v16, v233, v16, vcc
	v_cmp_le_i32_e32 vcc, v50, v239
	v_or_b32_e32 v50, 2, v222
	s_nop 0
	v_cndmask_b32_e32 v1, v233, v1, vcc
	v_cmp_le_i32_e32 vcc, v50, v239
	v_or_b32_e32 v50, 34, v222
	s_nop 0
	v_cndmask_b32_e32 v18, v233, v18, vcc
	v_cmp_le_i32_e32 vcc, v50, v239
	v_or_b32_e32 v50, 3, v222
	s_nop 0
	v_cndmask_b32_e32 v2, v233, v2, vcc
	v_cmp_le_i32_e32 vcc, v50, v239
	v_or_b32_e32 v50, 35, v222
	s_nop 0
	v_cndmask_b32_e32 v19, v233, v19, vcc
	v_cmp_le_i32_e32 vcc, v50, v239
	v_or_b32_e32 v50, 8, v222
	s_nop 0
	v_cndmask_b32_e32 v3, v233, v3, vcc
	v_cmp_le_i32_e32 vcc, v50, v239
	v_or_b32_e32 v50, 40, v222
	s_nop 0
	v_cndmask_b32_e32 v20, v233, v20, vcc
	v_cmp_le_i32_e32 vcc, v50, v239
	v_or_b32_e32 v50, 9, v222
	s_nop 0
	v_cndmask_b32_e32 v4, v233, v4, vcc
	v_cmp_le_i32_e32 vcc, v50, v239
	v_or_b32_e32 v50, 41, v222
	s_nop 0
	v_cndmask_b32_e32 v21, v233, v21, vcc
	v_cmp_le_i32_e32 vcc, v50, v239
	v_or_b32_e32 v50, 10, v222
	s_nop 0
	v_cndmask_b32_e32 v5, v233, v5, vcc
	v_cmp_le_i32_e32 vcc, v50, v239
	v_or_b32_e32 v50, 42, v222
	s_nop 0
	v_cndmask_b32_e32 v22, v233, v22, vcc
	v_cmp_le_i32_e32 vcc, v50, v239
	v_or_b32_e32 v50, 11, v222
	s_nop 0
	v_cndmask_b32_e32 v6, v233, v6, vcc
	v_cmp_le_i32_e32 vcc, v50, v239
	v_or_b32_e32 v50, 43, v222
	s_nop 0
	v_cndmask_b32_e32 v23, v233, v23, vcc
	v_cmp_le_i32_e32 vcc, v50, v239
	v_or_b32_e32 v50, 16, v222
	s_nop 0
	v_cndmask_b32_e32 v7, v233, v7, vcc
	v_cmp_le_i32_e32 vcc, v50, v239
	v_or_b32_e32 v50, 48, v222
	s_nop 0
	v_cndmask_b32_e32 v24, v233, v24, vcc
	v_cmp_le_i32_e32 vcc, v50, v239
	v_or_b32_e32 v50, 17, v222
	s_nop 0
	v_cndmask_b32_e32 v8, v233, v8, vcc
	v_cmp_le_i32_e32 vcc, v50, v239
	v_or_b32_e32 v50, 49, v222
	s_nop 0
	v_cndmask_b32_e32 v25, v233, v25, vcc
	v_cmp_le_i32_e32 vcc, v50, v239
	v_or_b32_e32 v50, 18, v222
	s_nop 0
	v_cndmask_b32_e32 v9, v233, v9, vcc
	v_cmp_le_i32_e32 vcc, v50, v239
	v_or_b32_e32 v50, 50, v222
	s_nop 0
	v_cndmask_b32_e32 v26, v233, v26, vcc
	v_cmp_le_i32_e32 vcc, v50, v239
	v_or_b32_e32 v50, 19, v222
	s_nop 0
	v_cndmask_b32_e32 v10, v233, v10, vcc
	v_cmp_le_i32_e32 vcc, v50, v239
	v_or_b32_e32 v50, 51, v222
	s_nop 0
	v_cndmask_b32_e32 v27, v233, v27, vcc
	v_cmp_le_i32_e32 vcc, v50, v239
	v_or_b32_e32 v50, 24, v222
	s_nop 0
	v_cndmask_b32_e32 v11, v233, v11, vcc
	v_cmp_le_i32_e32 vcc, v50, v239
	v_or_b32_e32 v50, 56, v222
	s_nop 0
	v_cndmask_b32_e32 v28, v233, v28, vcc
	v_cmp_le_i32_e32 vcc, v50, v239
	v_or_b32_e32 v50, 25, v222
	s_nop 0
	v_cndmask_b32_e32 v12, v233, v12, vcc
	v_cmp_le_i32_e32 vcc, v50, v239
	v_or_b32_e32 v50, 57, v222
	s_nop 0
	v_cndmask_b32_e32 v29, v233, v29, vcc
	v_cmp_le_i32_e32 vcc, v50, v239
	v_or_b32_e32 v50, 26, v222
	s_nop 0
	v_cndmask_b32_e32 v13, v233, v13, vcc
	v_cmp_le_i32_e32 vcc, v50, v239
	v_or_b32_e32 v50, 58, v222
	s_nop 0
	v_cndmask_b32_e32 v30, v233, v30, vcc
	v_cmp_le_i32_e32 vcc, v50, v239
	v_or_b32_e32 v50, 27, v222
	s_nop 0
	v_cndmask_b32_e32 v14, v233, v14, vcc
	v_cmp_le_i32_e32 vcc, v50, v239
	v_or_b32_e32 v50, 59, v222
	s_nop 0
	v_cndmask_b32_e32 v31, v233, v31, vcc
	v_cmp_le_i32_e32 vcc, v50, v239
	s_nop 1
	v_cndmask_b32_e32 v15, v233, v15, vcc

.LBB0_553:
	s_and_b32 s0, s68, 0x3fffffc0
	s_lshl_b32 s0, s0, 2
	s_add_i32 s0, s0, 0
	s_cmp_lg_u32 0, -1
	s_cselect_b32 s4, 0, 0
	s_addk_i32 s4, 0x6000
	v_add3_u32 v49, v242, s4, v240
	v_add_u32_e32 v50, s73, v243
	ds_read_b64_tr_b16 v[124:125], v50 offset:24576
	ds_read_b64_tr_b16 v[126:127], v50 offset:25088
	v_add_f32_e32 v51, v80, v81
	v_add_f32_e32 v51, v82, v51
	v_add_f32_e32 v51, v83, v51
	v_add_f32_e32 v51, v84, v51
	v_add_f32_e32 v51, v85, v51
	v_cvt_pk_bf16_f32 v156, v80, v81
	v_cvt_pk_bf16_f32 v157, v82, v83
	s_waitcnt lgkmcnt(9)
	v_mfma_f32_32x32x16_bf16 v[96:111], v[114:117], v[140:143], v[32:47]
	ds_read_b64_tr_b16 v[120:121], v50 offset:28672
	ds_read_b64_tr_b16 v[122:123], v50 offset:29184
	s_waitcnt lgkmcnt(10)
	v_mfma_f32_32x32x16_bf16 v[32:47], v[184:187], v[140:143], v[32:47]
	v_add_f32_e32 v51, v86, v51
	v_add_f32_e32 v51, v87, v51
	v_add_f32_e32 v51, v88, v51
	v_add_f32_e32 v51, v89, v51
	v_cvt_pk_bf16_f32 v158, v84, v85
	v_cvt_pk_bf16_f32 v159, v86, v87
	ds_read_b64_tr_b16 v[116:117], v50 offset:25600
	ds_read_b64_tr_b16 v[118:119], v50 offset:26112
	v_add_f32_e32 v51, v90, v51
	v_add_f32_e32 v51, v91, v51
	v_add_f32_e32 v51, v92, v51
	v_add_f32_e32 v51, v93, v51
	v_cvt_pk_bf16_f32 v152, v88, v89
	v_cvt_pk_bf16_f32 v153, v90, v91
	s_waitcnt lgkmcnt(11)
	v_mfma_f32_32x32x16_bf16 v[96:111], v[180:183], v[136:139], v[96:111]
	ds_read_b64_tr_b16 v[112:113], v50 offset:29696
	ds_read_b64_tr_b16 v[114:115], v50 offset:30208
	s_waitcnt lgkmcnt(12)
	v_mfma_f32_32x32x16_bf16 v[32:47], v[176:179], v[136:139], v[32:47]
	v_add_f32_e32 v51, v94, v51
	v_add_f32_e32 v51, v95, v51
	v_add_f32_e32 v51, v64, v51
	v_add_f32_e32 v51, v65, v51
	v_cvt_pk_bf16_f32 v154, v92, v93
	v_cvt_pk_bf16_f32 v155, v94, v95
	ds_read_b64_tr_b16 v[88:89], v50 offset:26624
	ds_read_b64_tr_b16 v[90:91], v50 offset:27136
	v_add_f32_e32 v51, v66, v51
	v_add_f32_e32 v51, v67, v51
	v_add_f32_e32 v51, v68, v51
	v_add_f32_e32 v51, v69, v51
	v_cvt_pk_bf16_f32 v148, v64, v65
	v_cvt_pk_bf16_f32 v149, v66, v67
	s_waitcnt lgkmcnt(13)
	v_mfma_f32_32x32x16_bf16 v[96:111], v[172:175], v[132:135], v[96:111]
	ds_read_b64_tr_b16 v[84:85], v50 offset:30720
	ds_read_b64_tr_b16 v[86:87], v50 offset:31232
	s_waitcnt lgkmcnt(14)
	v_mfma_f32_32x32x16_bf16 v[32:47], v[164:167], v[132:135], v[32:47]
	v_add_f32_e32 v51, v70, v51
	v_add_f32_e32 v51, v71, v51
	v_add_f32_e32 v51, v72, v51
	v_add_f32_e32 v51, v73, v51
	v_cvt_pk_bf16_f32 v150, v68, v69
	v_cvt_pk_bf16_f32 v151, v70, v71
	ds_read_b64_tr_b16 v[80:81], v50 offset:27648
	ds_read_b64_tr_b16 v[82:83], v50 offset:28160
	v_add_f32_e32 v51, v74, v51
	v_add_f32_e32 v51, v75, v51
	v_add_f32_e32 v51, v76, v51
	v_add_f32_e32 v51, v77, v51
	v_cvt_pk_bf16_f32 v144, v72, v73
	v_cvt_pk_bf16_f32 v145, v74, v75
	s_waitcnt lgkmcnt(14)
	v_mfma_f32_32x32x16_bf16 v[96:111], v[168:171], v[128:131], v[96:111]
	ds_read_b64_tr_b16 v[66:67], v50 offset:31744
	ds_read_b64_tr_b16 v[68:69], v50 offset:32256
	v_mfma_f32_32x32x16_bf16 v[32:47], v[160:163], v[128:131], v[32:47]
	v_add_f32_e32 v50, v78, v51
	v_add_f32_e32 v50, v79, v50
	v_add_f32_e32 v92, 0, v50
	v_cvt_pk_bf16_f32 v146, v76, v77
	v_cvt_pk_bf16_f32 v147, v78, v79
	v_or_b32_e32 v51, 0xe0, v222
	v_or_b32_e32 v50, 0xc0, v222
	v_cmp_le_i32_e32 vcc, v51, v239
	s_nop 3
	v_cndmask_b32_e32 v54, v233, v32, vcc
	v_cmp_lt_i32_e32 vcc, v50, v239
	v_or_b32_e32 v32, 0xe1, v222
	s_nop 0
	v_cndmask_b32_e32 v55, v233, v97, vcc
	v_cmp_le_i32_e32 vcc, v50, v239
	s_nop 1
	v_cndmask_b32_e32 v93, v233, v96, vcc
	v_cmp_le_i32_e32 vcc, v32, v239
	v_or_b32_e32 v32, 0xc2, v222
	s_nop 0
	v_cndmask_b32_e32 v94, v233, v33, vcc
	v_cmp_le_i32_e32 vcc, v32, v239
	v_or_b32_e32 v32, 0xe2, v222
	s_nop 0
	v_cndmask_b32_e32 v95, v233, v98, vcc
	v_cmp_le_i32_e32 vcc, v32, v239
	v_or_b32_e32 v32, 0xc3, v222
	s_nop 0
	v_cndmask_b32_e32 v96, v233, v34, vcc
	v_cmp_le_i32_e32 vcc, v32, v239
	v_or_b32_e32 v32, 0xe3, v222
	s_nop 0
	v_cndmask_b32_e32 v97, v233, v99, vcc
	v_cmp_le_i32_e32 vcc, v32, v239
	v_or_b32_e32 v32, 0xc8, v222
	v_lshl_add_u32 v99, v222, 2, s67
	v_cndmask_b32_e32 v98, v233, v35, vcc
	v_cmp_le_i32_e32 vcc, v32, v239
	v_or_b32_e32 v32, 0xe8, v222
	s_nop 0
	v_cndmask_b32_e32 v50, v233, v100, vcc
	v_cmp_le_i32_e32 vcc, v32, v239
	v_or_b32_e32 v32, 0xc9, v222
	s_nop 0
	v_cndmask_b32_e32 v52, v233, v36, vcc
	v_cmp_le_i32_e32 vcc, v32, v239
	v_or_b32_e32 v32, 0xe9, v222
	v_or_b32_e32 v36, 0xfb, v222
	v_cndmask_b32_e32 v51, v233, v101, vcc
	v_cmp_le_i32_e32 vcc, v32, v239
	v_or_b32_e32 v32, 0xca, v222
	s_nop 0
	v_cndmask_b32_e32 v53, v233, v37, vcc
	v_cmp_le_i32_e32 vcc, v32, v239
	v_or_b32_e32 v32, 0xea, v222
	s_nop 0
	v_cndmask_b32_e32 v56, v233, v102, vcc
	v_cmp_le_i32_e32 vcc, v32, v239
	v_or_b32_e32 v32, 0xcb, v222
	s_nop 0
	v_cndmask_b32_e32 v58, v233, v38, vcc
	v_cmp_le_i32_e32 vcc, v32, v239
	v_or_b32_e32 v32, 0xeb, v222
	s_nop 0
	v_cndmask_b32_e32 v57, v233, v103, vcc
	v_cmp_le_i32_e32 vcc, v32, v239
	v_or_b32_e32 v32, 0xd0, v222
	s_nop 0
	v_cndmask_b32_e32 v59, v233, v39, vcc
	v_cmp_le_i32_e32 vcc, v32, v239
	v_or_b32_e32 v32, 0xf0, v222
	s_nop 0
	v_cndmask_b32_e32 v60, v233, v104, vcc
	v_cmp_le_i32_e32 vcc, v32, v239
	v_or_b32_e32 v32, 0xd1, v222
	s_nop 0
	v_cndmask_b32_e32 v62, v233, v40, vcc
	v_cmp_le_i32_e32 vcc, v32, v239
	v_or_b32_e32 v32, 0xf1, v222
	s_nop 0
	v_cndmask_b32_e32 v61, v233, v105, vcc
	v_cmp_le_i32_e32 vcc, v32, v239
	v_or_b32_e32 v32, 0xd2, v222
	s_nop 0
	v_cndmask_b32_e32 v63, v233, v41, vcc
	v_cmp_le_i32_e32 vcc, v32, v239
	v_or_b32_e32 v32, 0xf2, v222
	s_nop 0
	v_cndmask_b32_e32 v64, v233, v106, vcc
	v_cmp_le_i32_e32 vcc, v32, v239
	v_or_b32_e32 v32, 0xd3, v222
	s_nop 0
	v_cndmask_b32_e32 v70, v233, v42, vcc
	v_cmp_le_i32_e32 vcc, v32, v239
	v_or_b32_e32 v32, 0xf3, v222
	s_nop 0
	v_cndmask_b32_e32 v65, v233, v107, vcc
	v_cmp_le_i32_e32 vcc, v32, v239
	v_or_b32_e32 v32, 0xd8, v222
	s_nop 0
	v_cndmask_b32_e32 v71, v233, v43, vcc
	v_cmp_le_i32_e32 vcc, v32, v239
	v_or_b32_e32 v32, 0xf8, v222
	s_nop 0
	v_cndmask_b32_e32 v72, v233, v108, vcc
	v_cmp_le_i32_e32 vcc, v32, v239
	v_or_b32_e32 v32, 0xd9, v222
	s_nop 0
	v_cndmask_b32_e32 v74, v233, v44, vcc
	v_cmp_le_i32_e32 vcc, v32, v239
	v_or_b32_e32 v32, 0xf9, v222
	s_nop 0
	v_cndmask_b32_e32 v73, v233, v109, vcc
	v_cmp_le_i32_e32 vcc, v32, v239
	v_or_b32_e32 v32, 0xda, v222
	s_nop 0
	v_cndmask_b32_e32 v75, v233, v45, vcc
	v_cmp_le_i32_e32 vcc, v32, v239
	v_or_b32_e32 v32, 0xfa, v222
	s_nop 0
	v_cndmask_b32_e32 v76, v233, v110, vcc
	v_cmp_le_i32_e32 vcc, v32, v239
	v_or_b32_e32 v32, 0xdb, v222
	s_nop 0
	v_cndmask_b32_e32 v78, v233, v46, vcc
	v_cmp_le_i32_e32 vcc, v32, v239
	ds_read_b128 v[32:35], v99 offset:768
	s_waitcnt lgkmcnt(0)
	v_add_f32_e32 v93, v32, v93
	v_cndmask_b32_e32 v77, v233, v111, vcc
	v_cmp_le_i32_e32 vcc, v36, v239
	ds_read_b128 v[36:39], v99 offset:896
	ds_read_b128 v[40:43], v99 offset:800
	v_add_f32_e32 v100, v33, v55
	v_add_f32_e32 v95, v34, v95
	v_add_f32_e32 v97, v35, v97
	ds_read_b128 v[32:35], v99 offset:928
	v_cndmask_b32_e32 v79, v233, v47, vcc
	s_waitcnt lgkmcnt(2)
	v_add_f32_e32 v101, v36, v54
	v_add_f32_e32 v94, v37, v94
	v_add_f32_e32 v96, v38, v96
	v_add_f32_e32 v98, v39, v98
	s_waitcnt lgkmcnt(1)
	v_pk_add_f32 v[54:55], v[40:41], v[50:51]
	v_pk_add_f32 v[56:57], v[42:43], v[56:57]
	ds_read_b128 v[40:43], v99 offset:832
	s_waitcnt lgkmcnt(1)
	v_pk_add_f32 v[36:37], v[32:33], v[52:53]
	v_pk_add_f32 v[38:39], v[34:35], v[58:59]
	ds_read_b128 v[32:35], v99 offset:960
	ds_read_b128 v[44:47], v99 offset:864
	ds_read_b128 v[50:53], v99 offset:992
	s_waitcnt lgkmcnt(3)
	v_pk_add_f32 v[58:59], v[40:41], v[60:61]
	v_pk_add_f32 v[60:61], v[42:43], v[64:65]
	s_waitcnt lgkmcnt(2)
	v_pk_add_f32 v[40:41], v[32:33], v[62:63]
	v_pk_add_f32 v[42:43], v[34:35], v[70:71]
	s_waitcnt lgkmcnt(1)
	v_pk_add_f32 v[62:63], v[44:45], v[72:73]
	v_pk_add_f32 v[64:65], v[46:47], v[76:77]
	s_waitcnt lgkmcnt(0)
	v_pk_add_f32 v[44:45], v[50:51], v[74:75]
	v_pk_add_f32 v[46:47], v[52:53], v[78:79]
	v_mfma_f32_32x32x16_bf16 v[0:15], v[156:159], v[124:127], v[0:15]
	v_exp_f32_e32 v50, v93
	v_exp_f32_e32 v51, v100
	v_exp_f32_e32 v52, v95
	v_exp_f32_e32 v53, v97
	v_mfma_f32_32x32x16_bf16 v[16:31], v[156:159], v[120:123], v[16:31]
	v_exp_f32_e32 v54, v54
	v_exp_f32_e32 v55, v55
	v_exp_f32_e32 v56, v56
	v_exp_f32_e32 v57, v57
	v_mfma_f32_32x32x16_bf16 v[0:15], v[152:155], v[116:119], v[0:15]
	v_exp_f32_e32 v58, v58
	v_exp_f32_e32 v59, v59
	v_exp_f32_e32 v60, v60
	v_exp_f32_e32 v61, v61
	v_mfma_f32_32x32x16_bf16 v[16:31], v[152:155], v[112:115], v[16:31]
	v_exp_f32_e32 v62, v62
	v_exp_f32_e32 v63, v63
	v_exp_f32_e32 v64, v64
	v_exp_f32_e32 v65, v65
	v_mfma_f32_32x32x16_bf16 v[0:15], v[148:151], v[88:91], v[0:15]
	v_exp_f32_e32 v32, v101
	v_exp_f32_e32 v33, v94
	v_exp_f32_e32 v34, v96
	v_exp_f32_e32 v35, v98
	v_mfma_f32_32x32x16_bf16 v[16:31], v[148:151], v[84:87], v[16:31]
	v_exp_f32_e32 v36, v36
	v_exp_f32_e32 v37, v37
	v_exp_f32_e32 v38, v38
	v_exp_f32_e32 v39, v39
	v_mfma_f32_32x32x16_bf16 v[0:15], v[144:147], v[80:83], v[0:15]
	v_exp_f32_e32 v40, v40
	v_exp_f32_e32 v41, v41
	v_exp_f32_e32 v42, v42
	v_exp_f32_e32 v43, v43
	v_mfma_f32_32x32x16_bf16 v[16:31], v[144:147], v[66:69], v[16:31]
	v_exp_f32_e32 v44, v44
	v_exp_f32_e32 v45, v45
	v_exp_f32_e32 v46, v46
	v_exp_f32_e32 v47, v47
	v_add_f32_e32 v66, v50, v51
	v_add_f32_e32 v66, v52, v66
	v_add_f32_e32 v66, v53, v66
	v_add_f32_e32 v66, v54, v66
	v_add_f32_e32 v66, v55, v66
	v_add_f32_e32 v66, v56, v66
	v_add_f32_e32 v66, v57, v66
	v_add_f32_e32 v66, v58, v66
	v_add_f32_e32 v66, v59, v66
	v_add_f32_e32 v66, v60, v66
	v_add_f32_e32 v66, v61, v66
	v_add_f32_e32 v66, v62, v66
	v_add_f32_e32 v66, v63, v66
	v_add_f32_e32 v66, v64, v66
	v_add_f32_e32 v66, v65, v66
	v_add_f32_e32 v66, v32, v66
	v_add_f32_e32 v66, v33, v66
	v_add_f32_e32 v66, v34, v66
	v_add_f32_e32 v66, v35, v66
	v_add_f32_e32 v66, v36, v66
	v_add_f32_e32 v66, v37, v66
	v_add_f32_e32 v66, v38, v66
	v_add_f32_e32 v66, v39, v66
	v_add_f32_e32 v66, v40, v66
	v_add_f32_e32 v66, v41, v66
	v_add_f32_e32 v66, v42, v66
	v_add_f32_e32 v66, v43, v66
	v_add_f32_e32 v66, v44, v66
	v_add_f32_e32 v66, v45, v66
	v_add_f32_e32 v66, v46, v66
	v_add_f32_e32 v66, v47, v66
	v_add_f32_e32 v48, v48, v92
	v_add_f32_e32 v48, v48, v66
	v_cvt_pk_bf16_f32 v32, v32, v33
	v_cvt_pk_bf16_f32 v50, v50, v51
	v_cvt_pk_bf16_f32 v51, v52, v53
	v_cvt_pk_bf16_f32 v52, v54, v55
	v_cvt_pk_bf16_f32 v53, v56, v57
	v_cvt_pk_bf16_f32 v54, v58, v59
	v_cvt_pk_bf16_f32 v55, v60, v61
	v_cvt_pk_bf16_f32 v56, v62, v63
	v_cvt_pk_bf16_f32 v57, v64, v65
	v_cvt_pk_bf16_f32 v33, v34, v35
	v_cvt_pk_bf16_f32 v34, v36, v37
	v_cvt_pk_bf16_f32 v35, v38, v39
	v_cvt_pk_bf16_f32 v36, v40, v41
	v_cvt_pk_bf16_f32 v37, v42, v43
	v_cvt_pk_bf16_f32 v38, v44, v45
	v_cvt_pk_bf16_f32 v39, v46, v47
	v_add3_u32 v49, v49, v238, s72
	ds_read_b64_tr_b16 v[40:41],v49 offset:0
	ds_read_b64_tr_b16 v[42:43],v49 offset:512
	ds_read_b64_tr_b16 v[44:45],v49 offset:1024
	ds_read_b64_tr_b16 v[46:47],v49 offset:1536
	ds_read_b64_tr_b16 v[58:59],v49 offset:2048
	ds_read_b64_tr_b16 v[60:61],v49 offset:2560
	ds_read_b64_tr_b16 v[62:63],v49 offset:3072
	ds_read_b64_tr_b16 v[64:65],v49 offset:3584
	s_waitcnt lgkmcnt(0)
	s_nop 0
	v_mfma_f32_32x32x16_bf16 v[0:15], v[50:53], v[40:43], v[0:15]
	ds_read_b64_tr_b16 v[40:41],v49 offset:4096
	ds_read_b64_tr_b16 v[42:43],v49 offset:4608
	v_mfma_f32_32x32x16_bf16 v[0:15], v[54:57], v[44:47], v[0:15]
	ds_read_b64_tr_b16 v[44:45],v49 offset:5120
	ds_read_b64_tr_b16 v[46:47],v49 offset:5632
	v_mfma_f32_32x32x16_bf16 v[0:15], v[32:35], v[58:61], v[0:15]
	ds_read_b64_tr_b16 v[58:59],v49 offset:6144
	ds_read_b64_tr_b16 v[60:61],v49 offset:6656
	ds_read_b64_tr_b16 v[66:67],v49 offset:7168
	ds_read_b64_tr_b16 v[68:69],v49 offset:7680
	s_waitcnt lgkmcnt(0)
	v_mfma_f32_32x32x16_bf16 v[0:15], v[36:39], v[62:65], v[0:15]
	v_mfma_f32_32x32x16_bf16 v[16:31], v[50:53], v[40:43], v[16:31]
	v_cmp_gt_u32_e32 vcc, 32, v253
	v_mfma_f32_32x32x16_bf16 v[16:31], v[54:57], v[44:47], v[16:31]
	v_mfma_f32_32x32x16_bf16 v[16:31], v[32:35], v[58:61], v[16:31]
	v_mov_b32_e32 v32, v48
	s_nop 1
	v_permlane32_swap_b32_e32 v48, v32
	v_mfma_f32_32x32x16_bf16 v[16:31], v[36:39], v[66:69], v[16:31]
	s_and_saveexec_b64 s[4:5], vcc
	v_lshl_add_u32 v33, v254, 2, s0
	v_add_f32_e32 v32, v48, v32
	ds_write_b32 v33, v32 offset:49280
	s_or_b64 exec, exec, s[4:5]
	s_add_i32 s67, s65, 1
	s_lshr_b32 s71, s67, 1
	s_mul_i32 s71, s71, s84
	v_readlane_b32 s72, v255, 0
	s_mov_b64 s[100:101], 0
	s_add_i32 s71, s71, s72
	s_cmpk_lt_i32 s71, 0x200
	s_cbranch_scc0 .Lattn_pf_done_e
	s_ashr_i32 s72, s71, 2
	s_lshl_b32 s73, s71, 8
	s_and_b32 s73, s73, 0x300
	s_and_b32 s74, s67, 1
	s_xor_b32 s75, s73, 0x700
	s_cmp_eq_u32 s74, 0
	s_cselect_b32 s73, s75, s73
	s_add_i32 s74, s73, 0x100
	v_add_u32_e32 v50, s33, v252
	v_lshlrev_b32_e32 v51, 2, v50
	v_lshlrev_b32_e32 v52, 4, v50
	v_cmp_gt_i32_e32 vcc, s74, v51
	s_lshl_b32 s75, s72, 13
	s_add_u32 s80, s18, s75
	s_addc_u32 s81, s19, 0
	s_and_saveexec_b64 s[76:77], vcc
	s_mov_b64 s[100:101], exec
	global_load_dwordx4 v[100:103], v52, s[80:81]
	v_add_u32_e32 v104, 0x14800, v52
	s_mov_b64 exec, s[76:77]
	s_lshr_b32 s54, s72, 3
	s_and_b32 s55, s72, 7
	s_lshl_b32 s75, s54, 11
	s_or_b32 s75, s75, s73
	s_lshr_b32 s81, s33, 1
	s_add_i32 s75, s75, s81
	s_lshl_b32 s75, s75, 10
	s_lshl_b32 s80, s55, 7
	s_add_i32 s75, s75, s80
	s_add_u32 s80, s3, s75
	s_addc_u32 s81, s66, 0
	v_lshlrev_b32_e32 v50, 10, v254
	v_lshl_or_b32 v50, v232, 4, v50
	global_load_dwordx4 v[140:143], v50, s[80:81] nt
	global_load_dwordx4 v[136:139], v50, s[80:81] offset:32 nt
	global_load_dwordx4 v[132:135], v50, s[80:81] offset:64 nt
	global_load_dwordx4 v[128:131], v50, s[80:81] offset:96 nt
	s_lshl_b32 s56, s54, 21
	s_lshl_b32 s57, s55, 7
	s_add_i32 s56, s56, s57
	s_add_u32 s82, s62, s56
	s_addc_u32 s83, s63, 0
	s_add_u32 s94, s20, s56
	s_addc_u32 s95, s21, 0
	s_add_u32 s88, s82, 0x10000
	s_addc_u32 s89, s83, 0
	s_add_u32 s92, s82, 0x20000
	s_addc_u32 s93, s83, 0
	s_lshr_b32 s57, s33, 2
	v_lshl_add_u32 v53, v253, 10, s57
	s_and_b32 s59, s57, 48
	v_bfe_u32 v54, v252, 2, 4
	v_or_b32_e32 v54, s59, v54
	s_lshr_b32 s59, s33, 8
	v_and_b32_e32 v55, 3, v252
	s_lshl_b32 s59, s59, 6
	v_lshlrev_b32_e32 v55, 4, v55
	v_lshl_add_u32 v54, v54, 10, s59
	s_lshl_b32 s32, s33, 4
	v_add_u32_e32 v54, v54, v55
	s_barrier
	s_mov_b32 s27, m0
	s_mov_b32 m0, s32
	s_nop 0
	global_load_lds_dwordx4 v53, s[82:83]
	s_add_i32 m0, s32, 0x6000
	s_nop 0
	global_load_lds_dwordx4 v54, s[94:95]
	s_add_i32 m0, s32, 0x2000
	s_nop 0
	global_load_lds_dwordx4 v53, s[88:89]
	s_add_i32 m0, s32, 0x4000
	s_nop 0
	global_load_lds_dwordx4 v53, s[92:93]
	s_mov_b32 m0, s27
.Lattn_pf_done_e:
	s_waitcnt lgkmcnt(0)
	v_lshl_add_u32 v40, v222, 2, s0
	ds_read_b128 v[32:35], v40 offset:49280
	ds_read_b128 v[36:39], v40 offset:49312
	s_lshl_b64 s[4:5], s[42:43], 11
	s_add_u32 s0, s60, s4
	s_addc_u32 s5, s61, s5
	s_waitcnt lgkmcnt(1)
	v_rcp_f32_e32 v41, v32
	s_lshl_b32 s4, s45, 12
	v_rcp_f32_e32 v42, v33
	v_rcp_f32_e32 v43, v34
	v_rcp_f32_e32 v44, v35
	s_waitcnt lgkmcnt(0)
	v_rcp_f32_e32 v45, v36
	ds_read_b128 v[32:35], v40 offset:49344
	v_rcp_f32_e32 v46, v37
	v_rcp_f32_e32 v47, v38
	v_rcp_f32_e32 v48, v39
	ds_read_b128 v[36:39], v40 offset:49376
	s_add_i32 s26, s4, 0
	v_lshlrev_b32_e32 v40, 1, v254
	v_lshlrev_b32_e32 v49, 9, v232
	v_mul_f32_e32 v0, v0, v41
	v_add3_u32 v40, s26, v40, v49
	v_cvt_pk_bf16_f32 v0, v0, s0
	ds_write_b16 v40, v0 offset:51200
	v_mul_f32_e32 v0, v16, v41
	v_cvt_pk_bf16_f32 v0, v0, s0
	ds_write_b16 v40, v0 offset:51264
	v_mul_f32_e32 v0, v1, v42
	v_cvt_pk_bf16_f32 v0, v0, s0
	ds_write_b16 v40, v0 offset:51328
	v_mul_f32_e32 v0, v17, v42
	v_cvt_pk_bf16_f32 v0, v0, s0
	ds_write_b16 v40, v0 offset:51392
	v_mul_f32_e32 v0, v2, v43
	v_cvt_pk_bf16_f32 v0, v0, s0
	ds_write_b16 v40, v0 offset:51456
	v_mul_f32_e32 v0, v18, v43
	v_cvt_pk_bf16_f32 v0, v0, s0
	ds_write_b16 v40, v0 offset:51520
	v_mul_f32_e32 v0, v3, v44
	v_cvt_pk_bf16_f32 v0, v0, s0
	ds_write_b16 v40, v0 offset:51584
	v_mul_f32_e32 v0, v19, v44
	v_cvt_pk_bf16_f32 v0, v0, s0
	ds_write_b16 v40, v0 offset:51648
	v_mul_f32_e32 v0, v4, v45
	v_cvt_pk_bf16_f32 v0, v0, s0
	ds_write_b16 v40, v0 offset:52224
	v_mul_f32_e32 v0, v20, v45
	v_cvt_pk_bf16_f32 v0, v0, s0
	ds_write_b16 v40, v0 offset:52288
	v_mul_f32_e32 v0, v5, v46
	v_cvt_pk_bf16_f32 v0, v0, s0
	ds_write_b16 v40, v0 offset:52352
	v_mul_f32_e32 v0, v21, v46
	v_cvt_pk_bf16_f32 v0, v0, s0
	ds_write_b16 v40, v0 offset:52416
	v_mul_f32_e32 v0, v6, v47
	v_cvt_pk_bf16_f32 v0, v0, s0
	ds_write_b16 v40, v0 offset:52480
	v_mul_f32_e32 v0, v22, v47
	v_cvt_pk_bf16_f32 v0, v0, s0
	s_waitcnt lgkmcnt(14)
	v_rcp_f32_e32 v32, v32
	ds_write_b16 v40, v0 offset:52544
	v_mul_f32_e32 v0, v7, v48
	v_cvt_pk_bf16_f32 v0, v0, s0
	ds_write_b16 v40, v0 offset:52608
	v_mul_f32_e32 v0, v23, v48
	v_cvt_pk_bf16_f32 v0, v0, s0
	v_rcp_f32_e32 v33, v33
	ds_write_b16 v40, v0 offset:52672
	v_mul_f32_e32 v0, v8, v32
	v_cvt_pk_bf16_f32 v0, v0, s0
	ds_write_b16 v40, v0 offset:53248
	v_mul_f32_e32 v0, v24, v32
	v_cvt_pk_bf16_f32 v0, v0, s0
	v_rcp_f32_e32 v34, v34
	ds_write_b16 v40, v0 offset:53312
	v_mul_f32_e32 v0, v9, v33
	v_cvt_pk_bf16_f32 v0, v0, s0
	ds_write_b16 v40, v0 offset:53376
	v_mul_f32_e32 v0, v25, v33
	v_cvt_pk_bf16_f32 v0, v0, s0
	v_rcp_f32_e32 v35, v35
	ds_write_b16 v40, v0 offset:53440
	v_mul_f32_e32 v0, v10, v34
	v_cvt_pk_bf16_f32 v0, v0, s0
	ds_write_b16 v40, v0 offset:53504
	v_mul_f32_e32 v0, v26, v34
	v_cvt_pk_bf16_f32 v0, v0, s0
	s_waitcnt lgkmcnt(14)
	v_rcp_f32_e32 v36, v36
	ds_write_b16 v40, v0 offset:53568
	v_mul_f32_e32 v0, v11, v35
	v_cvt_pk_bf16_f32 v0, v0, s0
	ds_write_b16 v40, v0 offset:53632
	v_mul_f32_e32 v0, v27, v35
	v_cvt_pk_bf16_f32 v0, v0, s0
	v_rcp_f32_e32 v37, v37
	ds_write_b16 v40, v0 offset:53696
	v_mul_f32_e32 v0, v12, v36
	v_cvt_pk_bf16_f32 v0, v0, s0
	ds_write_b16 v40, v0 offset:54272
	v_mul_f32_e32 v0, v28, v36
	v_cvt_pk_bf16_f32 v0, v0, s0
	v_rcp_f32_e32 v38, v38
	ds_write_b16 v40, v0 offset:54336
	v_mul_f32_e32 v0, v13, v37
	v_cvt_pk_bf16_f32 v0, v0, s0
	ds_write_b16 v40, v0 offset:54400
	v_mul_f32_e32 v0, v29, v37
	v_cvt_pk_bf16_f32 v0, v0, s0
	v_rcp_f32_e32 v39, v39
	ds_write_b16 v40, v0 offset:54464
	v_mul_f32_e32 v0, v14, v38
	v_cvt_pk_bf16_f32 v0, v0, s0
	ds_write_b16 v40, v0 offset:54528
	v_mul_f32_e32 v0, v30, v38
	v_cvt_pk_bf16_f32 v0, v0, s0
	ds_write_b16 v40, v0 offset:54592
	v_mul_f32_e32 v0, v15, v39
	v_cvt_pk_bf16_f32 v0, v0, s0
	ds_write_b16 v40, v0 offset:54656
	v_mul_f32_e32 v0, v31, v39
	v_and_b32_e32 v4, 7, v252
	v_cvt_pk_bf16_f32 v0, v0, s0
	v_lshlrev_b32_e32 v222, 4, v4
	ds_write_b16 v40, v0 offset:54720
	v_lshrrev_b32_e32 v2, 3, v253
	v_add_u32_e32 v3, s26, v222
	s_waitcnt lgkmcnt(0)
	v_cmp_eq_u32_e32 vcc, 0, v4
	v_lshl_add_u32 v4, v2, 7, v3
	ds_read_b128 v[4:7], v4 offset:51200
	s_add_u32 s4, s0, s50
	s_addc_u32 s5, s5, s51
	v_lshl_add_u64 v[0:1], s[4:5], 0, v[222:223]
	v_lshlrev_b32_e32 v222, 11, v2
	v_lshl_add_u64 v[8:9], v[0:1], 0, v[222:223]
	s_waitcnt lgkmcnt(0)
	global_store_dwordx4 v[8:9], v[4:7], off
	v_lshlrev_b32_e32 v8, 16, v4
	s_ashr_i32 s45, s44, 31
	v_and_b32_e32 v4, 0xffff0000, v4
	v_mul_f32_e32 v4, v4, v4
	v_fmac_f32_e32 v4, v8, v8
	v_lshlrev_b32_e32 v8, 16, v5
	v_and_b32_e32 v5, 0xffff0000, v5
	v_mul_f32_e32 v5, v5, v5
	v_fmac_f32_e32 v5, v8, v8
	v_add_f32_e32 v4, v4, v5
	v_lshlrev_b32_e32 v5, 16, v6
	v_and_b32_e32 v6, 0xffff0000, v6
	v_mul_f32_e32 v6, v6, v6
	v_fmac_f32_e32 v6, v5, v5
	v_add_f32_e32 v4, v6, v4
	v_and_b32_e32 v6, 0xffff0000, v7
	v_lshlrev_b32_e32 v5, 16, v7
	v_mul_f32_e32 v6, v6, v6
	v_fmac_f32_e32 v6, v5, v5
	v_add_f32_e32 v4, v6, v4
	s_lshl_b64 s[4:5], s[44:45], 2
	s_add_u32 s4, s8, s4
	v_add_f32_dpp v4, v4, v4 quad_perm:[1,0,3,2] row_mask:0xf bank_mask:0xf bound_ctrl:1
	s_addc_u32 s5, s9, s5
	s_nop 0
	v_add_f32_dpp v4, v4, v4 quad_perm:[2,3,0,1] row_mask:0xf bank_mask:0xf bound_ctrl:1
	s_nop 1
	v_mov_b32_dpp v5, v4 row_half_mirror row_mask:0xf bank_mask:0xf bound_ctrl:1
	s_and_saveexec_b64 s[44:45], vcc
	s_cbranch_execz .LBB0_557
	v_mov_b32_e32 v7, s43
	v_or_b32_e32 v6, s42, v2
	v_lshlrev_b64 v[6:7], 5, v[6:7]
	v_lshl_add_u64 v[6:7], s[4:5], 0, v[6:7]
	v_add_f32_e32 v4, v4, v5
	global_store_dword v[6:7], v4, off
